# w_in q/k epilogue rewritten by hand: batched sum-of-squares with ds_swizzle+permlane32 reduction, rope tables prefetched 3 rows ahead, packed f32 math
# speedup vs baseline: 1.0671x; 1.0016x over previous
.LBB0_465:
	s_cmp_eq_u32 s44, 2
	s_cselect_b64 s[8:9], -1, 0
	s_and_b64 s[10:11], s[8:9], s[18:19]
	s_mov_b64 s[58:59], -1
	s_andn2_b64 vcc, exec, s[10:11]
	v_cmp_gt_i32_e64 s[10:11], s81, v204
	s_cbranch_vccz .LBB0_483
	s_load_dwordx4 s[20:23], s[0:1], 0x38
	s_and_b64 s[14:15], s[8:9], exec
	v_readlane_b32 s48, v255, 40
	v_readlane_b32 s49, v255, 41
	v_lshlrev_b32_e32 v0, 2, v247
	s_waitcnt lgkmcnt(0)
	s_cselect_b32 s14, s22, s20
	s_cselect_b32 s13, s23, s21
	s_add_u32 s14, s14, s48
	s_addc_u32 s15, s13, s49
	global_load_dwordx4 v[142:145], v0, s[14:15]
	global_load_dwordx4 v[138:141], v0, s[14:15] offset:16
	global_load_dwordx4 v[134:137], v0, s[14:15] offset:128
	global_load_dwordx4 v[130:133], v0, s[14:15] offset:144
	v_readlane_b32 s22, v255, 57
	v_readlane_b32 s23, v255, 58
	v_and_b32_e32 v235, 0xfcf, v204
	v_lshlrev_b32_e32 v235, 7, v235
	v_add_u32_e32 v235, v235, v0
	v_add_u32_e32 v234, 0x1000, v235
	s_and_b64 s[14:15], s[8:9], exec
	s_cselect_b32 s21, 1.0, 0x3e38aa3b
	s_cmpk_lt_i32 s3, 0x4000
	s_cselect_b32 s20, 1, 0
	global_load_dwordx4 v[146:149], v235, s[78:79] offset:0
	global_load_dwordx4 v[150:153], v235, s[78:79] offset:16
	global_load_dwordx4 v[154:157], v235, s[22:23] offset:0
	global_load_dwordx4 v[158:161], v235, s[22:23] offset:16
	global_load_dwordx4 v[162:165], v235, s[78:79] offset:2048
	global_load_dwordx4 v[166:169], v235, s[78:79] offset:2064
	global_load_dwordx4 v[170:173], v235, s[22:23] offset:2048
	global_load_dwordx4 v[174:177], v235, s[22:23] offset:2064
	s_lshl_b32 s13, s44, 8
	v_readlane_b32 s14, v255, 52
	s_or_b32 s14, s13, s14
	s_ashr_i32 s15, s14, 31
	s_lshl_b64 s[14:15], s[14:15], 1
	s_add_u32 s27, s77, s14
	v_readlane_b32 s13, v255, 56
	s_addc_u32 s29, s13, s15
	s_add_i32 s13, s3, 0xffffc000
	s_lshr_b32 s14, s13, 8
	s_ashr_i32 s13, s3, 12
	s_mul_i32 s15, s13, 0x1100
	s_mulk_i32 s14, 0x1100
	s_addk_i32 s15, 0x100
	v_and_b32_e32 v0, 0xfcf, v204
	v_and_b32_e32 v237, 0xcf, v204
	v_add_u32_e32 v0, s15, v0
	v_or_b32_e32 v237, s14, v237
	v_cndmask_b32_e64 v0, v237, v0, s[10:11]
	v_cndmask_b32_e64 v236, v204, v0, s[8:9]
	s_and_b64 s[48:49], s[8:9], exec
	s_cselect_b32 s13, 8, 10
	s_cselect_b32 s49, s93, s29
	s_cselect_b32 s48, s85, s27
	v_lshlrev_b32_e32 v236, s13, v236
	v_lshl_add_u32 v236, v247, 1, v236
	v_pk_mul_f32 v[206:207], v[126:127], v[126:127]
	v_pk_fma_f32 v[206:207], v[128:129], v[128:129], v[206:207]
	v_pk_fma_f32 v[206:207], v[122:123], v[122:123], v[206:207]
	v_pk_fma_f32 v[206:207], v[124:125], v[124:125], v[206:207]
	v_pk_fma_f32 v[206:207], v[118:119], v[118:119], v[206:207]
	v_pk_fma_f32 v[206:207], v[120:121], v[120:121], v[206:207]
	v_pk_fma_f32 v[206:207], v[114:115], v[114:115], v[206:207]
	v_pk_fma_f32 v[206:207], v[116:117], v[116:117], v[206:207]
	v_pk_mul_f32 v[208:209], v[110:111], v[110:111]
	v_pk_fma_f32 v[208:209], v[112:113], v[112:113], v[208:209]
	v_pk_fma_f32 v[208:209], v[106:107], v[106:107], v[208:209]
	v_pk_fma_f32 v[208:209], v[108:109], v[108:109], v[208:209]
	v_pk_fma_f32 v[208:209], v[102:103], v[102:103], v[208:209]
	v_pk_fma_f32 v[208:209], v[104:105], v[104:105], v[208:209]
	v_pk_fma_f32 v[208:209], v[98:99], v[98:99], v[208:209]
	v_pk_fma_f32 v[208:209], v[100:101], v[100:101], v[208:209]
	v_pk_mul_f32 v[210:211], v[94:95], v[94:95]
	v_pk_fma_f32 v[210:211], v[96:97], v[96:97], v[210:211]
	v_pk_fma_f32 v[210:211], v[90:91], v[90:91], v[210:211]
	v_pk_fma_f32 v[210:211], v[92:93], v[92:93], v[210:211]
	v_pk_fma_f32 v[210:211], v[86:87], v[86:87], v[210:211]
	v_pk_fma_f32 v[210:211], v[88:89], v[88:89], v[210:211]
	v_pk_fma_f32 v[210:211], v[82:83], v[82:83], v[210:211]
	v_pk_fma_f32 v[210:211], v[84:85], v[84:85], v[210:211]
	v_pk_mul_f32 v[212:213], v[78:79], v[78:79]
	v_pk_fma_f32 v[212:213], v[80:81], v[80:81], v[212:213]
	v_pk_fma_f32 v[212:213], v[74:75], v[74:75], v[212:213]
	v_pk_fma_f32 v[212:213], v[76:77], v[76:77], v[212:213]
	v_pk_fma_f32 v[212:213], v[70:71], v[70:71], v[212:213]
	v_pk_fma_f32 v[212:213], v[72:73], v[72:73], v[212:213]
	v_pk_fma_f32 v[212:213], v[66:67], v[66:67], v[212:213]
	v_pk_fma_f32 v[212:213], v[68:69], v[68:69], v[212:213]
	v_pk_mul_f32 v[214:215], v[62:63], v[62:63]
	v_pk_fma_f32 v[214:215], v[64:65], v[64:65], v[214:215]
	v_pk_fma_f32 v[214:215], v[58:59], v[58:59], v[214:215]
	v_pk_fma_f32 v[214:215], v[60:61], v[60:61], v[214:215]
	v_pk_fma_f32 v[214:215], v[54:55], v[54:55], v[214:215]
	v_pk_fma_f32 v[214:215], v[56:57], v[56:57], v[214:215]
	v_pk_fma_f32 v[214:215], v[50:51], v[50:51], v[214:215]
	v_pk_fma_f32 v[214:215], v[52:53], v[52:53], v[214:215]
	v_pk_mul_f32 v[216:217], v[46:47], v[46:47]
	v_pk_fma_f32 v[216:217], v[48:49], v[48:49], v[216:217]
	v_pk_fma_f32 v[216:217], v[42:43], v[42:43], v[216:217]
	v_pk_fma_f32 v[216:217], v[44:45], v[44:45], v[216:217]
	v_pk_fma_f32 v[216:217], v[38:39], v[38:39], v[216:217]
	v_pk_fma_f32 v[216:217], v[40:41], v[40:41], v[216:217]
	v_pk_fma_f32 v[216:217], v[34:35], v[34:35], v[216:217]
	v_pk_fma_f32 v[216:217], v[36:37], v[36:37], v[216:217]
	v_pk_mul_f32 v[218:219], v[30:31], v[30:31]
	v_pk_fma_f32 v[218:219], v[32:33], v[32:33], v[218:219]
	v_pk_fma_f32 v[218:219], v[26:27], v[26:27], v[218:219]
	v_pk_fma_f32 v[218:219], v[28:29], v[28:29], v[218:219]
	v_pk_fma_f32 v[218:219], v[22:23], v[22:23], v[218:219]
	v_pk_fma_f32 v[218:219], v[24:25], v[24:25], v[218:219]
	v_pk_fma_f32 v[218:219], v[18:19], v[18:19], v[218:219]
	v_pk_fma_f32 v[218:219], v[20:21], v[20:21], v[218:219]
	v_pk_mul_f32 v[220:221], v[14:15], v[14:15]
	v_pk_fma_f32 v[220:221], v[16:17], v[16:17], v[220:221]
	v_pk_fma_f32 v[220:221], v[10:11], v[10:11], v[220:221]
	v_pk_fma_f32 v[220:221], v[12:13], v[12:13], v[220:221]
	v_pk_fma_f32 v[220:221], v[6:7], v[6:7], v[220:221]
	v_pk_fma_f32 v[220:221], v[8:9], v[8:9], v[220:221]
	v_pk_fma_f32 v[220:221], v[2:3], v[2:3], v[220:221]
	v_pk_fma_f32 v[220:221], v[4:5], v[4:5], v[220:221]
	v_add_f32_e32 v178, v206, v207
	v_add_f32_e32 v179, v208, v209
	v_add_f32_e32 v180, v210, v211
	v_add_f32_e32 v181, v212, v213
	v_add_f32_e32 v182, v214, v215
	v_add_f32_e32 v183, v216, v217
	v_add_f32_e32 v184, v218, v219
	v_add_f32_e32 v185, v220, v221
	ds_swizzle_b32 v206, v178 offset:0x401f
	ds_swizzle_b32 v208, v179 offset:0x401f
	ds_swizzle_b32 v210, v180 offset:0x401f
	ds_swizzle_b32 v212, v181 offset:0x401f
	ds_swizzle_b32 v214, v182 offset:0x401f
	ds_swizzle_b32 v216, v183 offset:0x401f
	ds_swizzle_b32 v218, v184 offset:0x401f
	ds_swizzle_b32 v220, v185 offset:0x401f
	s_waitcnt lgkmcnt(0)
	v_add_f32_e32 v178, v178, v206
	v_add_f32_e32 v179, v179, v208
	v_add_f32_e32 v180, v180, v210
	v_add_f32_e32 v181, v181, v212
	v_add_f32_e32 v182, v182, v214
	v_add_f32_e32 v183, v183, v216
	v_add_f32_e32 v184, v184, v218
	v_add_f32_e32 v185, v185, v220
	v_mov_b32_e32 v206, v178
	v_mov_b32_e32 v208, v179
	v_mov_b32_e32 v210, v180
	v_mov_b32_e32 v212, v181
	v_mov_b32_e32 v214, v182
	v_mov_b32_e32 v216, v183
	v_mov_b32_e32 v218, v184
	v_mov_b32_e32 v220, v185
	v_permlane32_swap_b32_e32 v178, v206
	v_permlane32_swap_b32_e32 v179, v208
	v_permlane32_swap_b32_e32 v180, v210
	v_permlane32_swap_b32_e32 v181, v212
	v_permlane32_swap_b32_e32 v182, v214
	v_permlane32_swap_b32_e32 v183, v216
	v_permlane32_swap_b32_e32 v184, v218
	v_permlane32_swap_b32_e32 v185, v220
	v_add_f32_e32 v178, v178, v206
	v_add_f32_e32 v179, v179, v208
	v_add_f32_e32 v180, v180, v210
	v_add_f32_e32 v181, v181, v212
	v_add_f32_e32 v182, v182, v214
	v_add_f32_e32 v183, v183, v216
	v_add_f32_e32 v184, v184, v218
	v_add_f32_e32 v185, v185, v220
	v_fmamk_f32 v178, v178, 0x3c800000, v190
	v_fmamk_f32 v179, v179, 0x3c800000, v190
	v_fmamk_f32 v180, v180, 0x3c800000, v190
	v_fmamk_f32 v181, v181, 0x3c800000, v190
	v_fmamk_f32 v182, v182, 0x3c800000, v190
	v_fmamk_f32 v183, v183, 0x3c800000, v190
	v_fmamk_f32 v184, v184, 0x3c800000, v190
	v_fmamk_f32 v185, v185, 0x3c800000, v190
	v_rsq_f32_e32 v178, v178
	v_rsq_f32_e32 v179, v179
	v_rsq_f32_e32 v180, v180
	v_rsq_f32_e32 v181, v181
	v_rsq_f32_e32 v182, v182
	v_rsq_f32_e32 v183, v183
	v_rsq_f32_e32 v184, v184
	v_rsq_f32_e32 v185, v185
	v_mul_f32_e32 v178, s21, v178
	v_mul_f32_e32 v179, s21, v179
	v_mul_f32_e32 v180, s21, v180
	v_mul_f32_e32 v181, s21, v181
	v_mul_f32_e32 v182, s21, v182
	v_mul_f32_e32 v183, s21, v183
	v_mul_f32_e32 v184, s21, v184
	v_mul_f32_e32 v185, s21, v185
	global_load_dwordx4 v[206:209], v234, s[78:79] offset:0
	global_load_dwordx4 v[210:213], v234, s[78:79] offset:16
	global_load_dwordx4 v[214:217], v234, s[22:23] offset:0
	global_load_dwordx4 v[218:221], v234, s[22:23] offset:16
	s_waitcnt vmcnt(8)
	v_pk_mul_f32 v[126:127], v[126:127], v[178:179] op_sel_hi:[1,0]
	v_pk_mul_f32 v[128:129], v[128:129], v[178:179] op_sel_hi:[1,0]
	v_pk_mul_f32 v[122:123], v[122:123], v[178:179] op_sel_hi:[1,0]
	v_pk_mul_f32 v[124:125], v[124:125], v[178:179] op_sel_hi:[1,0]
	v_pk_mul_f32 v[118:119], v[118:119], v[178:179] op_sel_hi:[1,0]
	v_pk_mul_f32 v[120:121], v[120:121], v[178:179] op_sel_hi:[1,0]
	v_pk_mul_f32 v[114:115], v[114:115], v[178:179] op_sel_hi:[1,0]
	v_pk_mul_f32 v[116:117], v[116:117], v[178:179] op_sel_hi:[1,0]
	v_pk_mul_f32 v[126:127], v[126:127], v[142:143]
	v_pk_mul_f32 v[128:129], v[128:129], v[144:145]
	v_pk_mul_f32 v[122:123], v[122:123], v[138:139]
	v_pk_mul_f32 v[124:125], v[124:125], v[140:141]
	v_pk_mul_f32 v[118:119], v[118:119], v[134:135]
	v_pk_mul_f32 v[120:121], v[120:121], v[136:137]
	v_pk_mul_f32 v[114:115], v[114:115], v[130:131]
	v_pk_mul_f32 v[116:117], v[116:117], v[132:133]
	s_cmp_eq_u32 s20, 0
	s_cbranch_scc1 .Lwin_norope_0
	v_pk_mul_f32 v[192:193], v[118:119], v[154:155]
	v_pk_mul_f32 v[194:195], v[120:121], v[156:157]
	v_pk_mul_f32 v[118:119], v[118:119], v[146:147]
	v_pk_mul_f32 v[120:121], v[120:121], v[148:149]
	v_pk_fma_f32 v[118:119], v[126:127], v[154:155], v[118:119]
	v_pk_fma_f32 v[120:121], v[128:129], v[156:157], v[120:121]
	v_pk_fma_f32 v[126:127], v[126:127], v[146:147], v[192:193] neg_lo:[0,0,1] neg_hi:[0,0,1]
	v_pk_fma_f32 v[128:129], v[128:129], v[148:149], v[194:195] neg_lo:[0,0,1] neg_hi:[0,0,1]
	v_pk_mul_f32 v[192:193], v[114:115], v[158:159]
	v_pk_mul_f32 v[194:195], v[116:117], v[160:161]
	v_pk_mul_f32 v[114:115], v[114:115], v[150:151]
	v_pk_mul_f32 v[116:117], v[116:117], v[152:153]
	v_pk_fma_f32 v[114:115], v[122:123], v[158:159], v[114:115]
	v_pk_fma_f32 v[116:117], v[124:125], v[160:161], v[116:117]
	v_pk_fma_f32 v[122:123], v[122:123], v[150:151], v[192:193] neg_lo:[0,0,1] neg_hi:[0,0,1]
	v_pk_fma_f32 v[124:125], v[124:125], v[152:153], v[194:195] neg_lo:[0,0,1] neg_hi:[0,0,1]
.Lwin_norope_0:
	v_cvt_pk_bf16_f32 v126, v126, v127
	v_cvt_pk_bf16_f32 v127, v128, v129
	v_cvt_pk_bf16_f32 v128, v122, v123
	v_cvt_pk_bf16_f32 v129, v124, v125
	v_cvt_pk_bf16_f32 v118, v118, v119
	v_cvt_pk_bf16_f32 v119, v120, v121
	v_cvt_pk_bf16_f32 v120, v114, v115
	v_cvt_pk_bf16_f32 v121, v116, v117
	global_store_dwordx4 v236, v[126:129], s[48:49]
	global_store_dwordx4 v236, v[118:121], s[48:49] offset:64
	v_add_u32_e32 v234, 0x1800, v235
	global_load_dwordx4 v[114:117], v234, s[78:79] offset:0
	global_load_dwordx4 v[118:121], v234, s[78:79] offset:16
	global_load_dwordx4 v[122:125], v234, s[22:23] offset:0
	global_load_dwordx4 v[126:129], v234, s[22:23] offset:16
	s_waitcnt vmcnt(10)
	v_pk_mul_f32 v[110:111], v[110:111], v[178:179] op_sel:[0,1] op_sel_hi:[1,1]
	v_pk_mul_f32 v[112:113], v[112:113], v[178:179] op_sel:[0,1] op_sel_hi:[1,1]
	v_pk_mul_f32 v[106:107], v[106:107], v[178:179] op_sel:[0,1] op_sel_hi:[1,1]
	v_pk_mul_f32 v[108:109], v[108:109], v[178:179] op_sel:[0,1] op_sel_hi:[1,1]
	v_pk_mul_f32 v[102:103], v[102:103], v[178:179] op_sel:[0,1] op_sel_hi:[1,1]
	v_pk_mul_f32 v[104:105], v[104:105], v[178:179] op_sel:[0,1] op_sel_hi:[1,1]
	v_pk_mul_f32 v[98:99], v[98:99], v[178:179] op_sel:[0,1] op_sel_hi:[1,1]
	v_pk_mul_f32 v[100:101], v[100:101], v[178:179] op_sel:[0,1] op_sel_hi:[1,1]
	v_pk_mul_f32 v[110:111], v[110:111], v[142:143]
	v_pk_mul_f32 v[112:113], v[112:113], v[144:145]
	v_pk_mul_f32 v[106:107], v[106:107], v[138:139]
	v_pk_mul_f32 v[108:109], v[108:109], v[140:141]
	v_pk_mul_f32 v[102:103], v[102:103], v[134:135]
	v_pk_mul_f32 v[104:105], v[104:105], v[136:137]
	v_pk_mul_f32 v[98:99], v[98:99], v[130:131]
	v_pk_mul_f32 v[100:101], v[100:101], v[132:133]
	s_cmp_eq_u32 s20, 0
	s_cbranch_scc1 .Lwin_norope_1
	v_pk_mul_f32 v[192:193], v[102:103], v[170:171]
	v_pk_mul_f32 v[194:195], v[104:105], v[172:173]
	v_pk_mul_f32 v[102:103], v[102:103], v[162:163]
	v_pk_mul_f32 v[104:105], v[104:105], v[164:165]
	v_pk_fma_f32 v[102:103], v[110:111], v[170:171], v[102:103]
	v_pk_fma_f32 v[104:105], v[112:113], v[172:173], v[104:105]
	v_pk_fma_f32 v[110:111], v[110:111], v[162:163], v[192:193] neg_lo:[0,0,1] neg_hi:[0,0,1]
	v_pk_fma_f32 v[112:113], v[112:113], v[164:165], v[194:195] neg_lo:[0,0,1] neg_hi:[0,0,1]
	v_pk_mul_f32 v[192:193], v[98:99], v[174:175]
	v_pk_mul_f32 v[194:195], v[100:101], v[176:177]
	v_pk_mul_f32 v[98:99], v[98:99], v[166:167]
	v_pk_mul_f32 v[100:101], v[100:101], v[168:169]
	v_pk_fma_f32 v[98:99], v[106:107], v[174:175], v[98:99]
	v_pk_fma_f32 v[100:101], v[108:109], v[176:177], v[100:101]
	v_pk_fma_f32 v[106:107], v[106:107], v[166:167], v[192:193] neg_lo:[0,0,1] neg_hi:[0,0,1]
	v_pk_fma_f32 v[108:109], v[108:109], v[168:169], v[194:195] neg_lo:[0,0,1] neg_hi:[0,0,1]
.Lwin_norope_1:
	v_cvt_pk_bf16_f32 v110, v110, v111
	v_cvt_pk_bf16_f32 v111, v112, v113
	v_cvt_pk_bf16_f32 v112, v106, v107
	v_cvt_pk_bf16_f32 v113, v108, v109
	v_cvt_pk_bf16_f32 v102, v102, v103
	v_cvt_pk_bf16_f32 v103, v104, v105
	v_cvt_pk_bf16_f32 v104, v98, v99
	v_cvt_pk_bf16_f32 v105, v100, v101
	s_lshl_b32 s27, 16, s13
	v_add_u32_e32 v237, s27, v236
	global_store_dwordx4 v237, v[110:113], s[48:49]
	global_store_dwordx4 v237, v[102:105], s[48:49] offset:64
	v_add_u32_e32 v234, 0x4000, v235
	global_load_dwordx4 v[98:101], v234, s[78:79] offset:0
	global_load_dwordx4 v[102:105], v234, s[78:79] offset:16
	global_load_dwordx4 v[106:109], v234, s[22:23] offset:0
	global_load_dwordx4 v[110:113], v234, s[22:23] offset:16
	s_waitcnt vmcnt(12)
	v_pk_mul_f32 v[94:95], v[94:95], v[180:181] op_sel_hi:[1,0]
	v_pk_mul_f32 v[96:97], v[96:97], v[180:181] op_sel_hi:[1,0]
	v_pk_mul_f32 v[90:91], v[90:91], v[180:181] op_sel_hi:[1,0]
	v_pk_mul_f32 v[92:93], v[92:93], v[180:181] op_sel_hi:[1,0]
	v_pk_mul_f32 v[86:87], v[86:87], v[180:181] op_sel_hi:[1,0]
	v_pk_mul_f32 v[88:89], v[88:89], v[180:181] op_sel_hi:[1,0]
	v_pk_mul_f32 v[82:83], v[82:83], v[180:181] op_sel_hi:[1,0]
	v_pk_mul_f32 v[84:85], v[84:85], v[180:181] op_sel_hi:[1,0]
	v_pk_mul_f32 v[94:95], v[94:95], v[142:143]
	v_pk_mul_f32 v[96:97], v[96:97], v[144:145]
	v_pk_mul_f32 v[90:91], v[90:91], v[138:139]
	v_pk_mul_f32 v[92:93], v[92:93], v[140:141]
	v_pk_mul_f32 v[86:87], v[86:87], v[134:135]
	v_pk_mul_f32 v[88:89], v[88:89], v[136:137]
	v_pk_mul_f32 v[82:83], v[82:83], v[130:131]
	v_pk_mul_f32 v[84:85], v[84:85], v[132:133]
	s_cmp_eq_u32 s20, 0
	s_cbranch_scc1 .Lwin_norope_2
	v_pk_mul_f32 v[192:193], v[86:87], v[214:215]
	v_pk_mul_f32 v[194:195], v[88:89], v[216:217]
	v_pk_mul_f32 v[86:87], v[86:87], v[206:207]
	v_pk_mul_f32 v[88:89], v[88:89], v[208:209]
	v_pk_fma_f32 v[86:87], v[94:95], v[214:215], v[86:87]
	v_pk_fma_f32 v[88:89], v[96:97], v[216:217], v[88:89]
	v_pk_fma_f32 v[94:95], v[94:95], v[206:207], v[192:193] neg_lo:[0,0,1] neg_hi:[0,0,1]
	v_pk_fma_f32 v[96:97], v[96:97], v[208:209], v[194:195] neg_lo:[0,0,1] neg_hi:[0,0,1]
	v_pk_mul_f32 v[192:193], v[82:83], v[218:219]
	v_pk_mul_f32 v[194:195], v[84:85], v[220:221]
	v_pk_mul_f32 v[82:83], v[82:83], v[210:211]
	v_pk_mul_f32 v[84:85], v[84:85], v[212:213]
	v_pk_fma_f32 v[82:83], v[90:91], v[218:219], v[82:83]
	v_pk_fma_f32 v[84:85], v[92:93], v[220:221], v[84:85]
	v_pk_fma_f32 v[90:91], v[90:91], v[210:211], v[192:193] neg_lo:[0,0,1] neg_hi:[0,0,1]
	v_pk_fma_f32 v[92:93], v[92:93], v[212:213], v[194:195] neg_lo:[0,0,1] neg_hi:[0,0,1]
.Lwin_norope_2:
	v_cvt_pk_bf16_f32 v94, v94, v95
	v_cvt_pk_bf16_f32 v95, v96, v97
	v_cvt_pk_bf16_f32 v96, v90, v91
	v_cvt_pk_bf16_f32 v97, v92, v93
	v_cvt_pk_bf16_f32 v86, v86, v87
	v_cvt_pk_bf16_f32 v87, v88, v89
	v_cvt_pk_bf16_f32 v88, v82, v83
	v_cvt_pk_bf16_f32 v89, v84, v85
	s_lshl_b32 s27, 32, s13
	v_add_u32_e32 v237, s27, v236
	global_store_dwordx4 v237, v[94:97], s[48:49]
	global_store_dwordx4 v237, v[86:89], s[48:49] offset:64
	v_add_u32_e32 v234, 0x4800, v235
	global_load_dwordx4 v[82:85], v234, s[78:79] offset:0
	global_load_dwordx4 v[86:89], v234, s[78:79] offset:16
	global_load_dwordx4 v[90:93], v234, s[22:23] offset:0
	global_load_dwordx4 v[94:97], v234, s[22:23] offset:16
	s_waitcnt vmcnt(12)
	v_pk_mul_f32 v[78:79], v[78:79], v[180:181] op_sel:[0,1] op_sel_hi:[1,1]
	v_pk_mul_f32 v[80:81], v[80:81], v[180:181] op_sel:[0,1] op_sel_hi:[1,1]
	v_pk_mul_f32 v[74:75], v[74:75], v[180:181] op_sel:[0,1] op_sel_hi:[1,1]
	v_pk_mul_f32 v[76:77], v[76:77], v[180:181] op_sel:[0,1] op_sel_hi:[1,1]
	v_pk_mul_f32 v[70:71], v[70:71], v[180:181] op_sel:[0,1] op_sel_hi:[1,1]
	v_pk_mul_f32 v[72:73], v[72:73], v[180:181] op_sel:[0,1] op_sel_hi:[1,1]
	v_pk_mul_f32 v[66:67], v[66:67], v[180:181] op_sel:[0,1] op_sel_hi:[1,1]
	v_pk_mul_f32 v[68:69], v[68:69], v[180:181] op_sel:[0,1] op_sel_hi:[1,1]
	v_pk_mul_f32 v[78:79], v[78:79], v[142:143]
	v_pk_mul_f32 v[80:81], v[80:81], v[144:145]
	v_pk_mul_f32 v[74:75], v[74:75], v[138:139]
	v_pk_mul_f32 v[76:77], v[76:77], v[140:141]
	v_pk_mul_f32 v[70:71], v[70:71], v[134:135]
	v_pk_mul_f32 v[72:73], v[72:73], v[136:137]
	v_pk_mul_f32 v[66:67], v[66:67], v[130:131]
	v_pk_mul_f32 v[68:69], v[68:69], v[132:133]
	s_cmp_eq_u32 s20, 0
	s_cbranch_scc1 .Lwin_norope_3
	v_pk_mul_f32 v[192:193], v[70:71], v[122:123]
	v_pk_mul_f32 v[194:195], v[72:73], v[124:125]
	v_pk_mul_f32 v[70:71], v[70:71], v[114:115]
	v_pk_mul_f32 v[72:73], v[72:73], v[116:117]
	v_pk_fma_f32 v[70:71], v[78:79], v[122:123], v[70:71]
	v_pk_fma_f32 v[72:73], v[80:81], v[124:125], v[72:73]
	v_pk_fma_f32 v[78:79], v[78:79], v[114:115], v[192:193] neg_lo:[0,0,1] neg_hi:[0,0,1]
	v_pk_fma_f32 v[80:81], v[80:81], v[116:117], v[194:195] neg_lo:[0,0,1] neg_hi:[0,0,1]
	v_pk_mul_f32 v[192:193], v[66:67], v[126:127]
	v_pk_mul_f32 v[194:195], v[68:69], v[128:129]
	v_pk_mul_f32 v[66:67], v[66:67], v[118:119]
	v_pk_mul_f32 v[68:69], v[68:69], v[120:121]
	v_pk_fma_f32 v[66:67], v[74:75], v[126:127], v[66:67]
	v_pk_fma_f32 v[68:69], v[76:77], v[128:129], v[68:69]
	v_pk_fma_f32 v[74:75], v[74:75], v[118:119], v[192:193] neg_lo:[0,0,1] neg_hi:[0,0,1]
	v_pk_fma_f32 v[76:77], v[76:77], v[120:121], v[194:195] neg_lo:[0,0,1] neg_hi:[0,0,1]
.Lwin_norope_3:
	v_cvt_pk_bf16_f32 v78, v78, v79
	v_cvt_pk_bf16_f32 v79, v80, v81
	v_cvt_pk_bf16_f32 v80, v74, v75
	v_cvt_pk_bf16_f32 v81, v76, v77
	v_cvt_pk_bf16_f32 v70, v70, v71
	v_cvt_pk_bf16_f32 v71, v72, v73
	v_cvt_pk_bf16_f32 v72, v66, v67
	v_cvt_pk_bf16_f32 v73, v68, v69
	s_lshl_b32 s27, 48, s13
	v_add_u32_e32 v237, s27, v236
	global_store_dwordx4 v237, v[78:81], s[48:49]
	global_store_dwordx4 v237, v[70:73], s[48:49] offset:64
	v_add_u32_e32 v234, 0x5000, v235
	global_load_dwordx4 v[66:69], v234, s[78:79] offset:0
	global_load_dwordx4 v[70:73], v234, s[78:79] offset:16
	global_load_dwordx4 v[74:77], v234, s[22:23] offset:0
	global_load_dwordx4 v[78:81], v234, s[22:23] offset:16
	s_waitcnt vmcnt(12)
	v_pk_mul_f32 v[62:63], v[62:63], v[182:183] op_sel_hi:[1,0]
	v_pk_mul_f32 v[64:65], v[64:65], v[182:183] op_sel_hi:[1,0]
	v_pk_mul_f32 v[58:59], v[58:59], v[182:183] op_sel_hi:[1,0]
	v_pk_mul_f32 v[60:61], v[60:61], v[182:183] op_sel_hi:[1,0]
	v_pk_mul_f32 v[54:55], v[54:55], v[182:183] op_sel_hi:[1,0]
	v_pk_mul_f32 v[56:57], v[56:57], v[182:183] op_sel_hi:[1,0]
	v_pk_mul_f32 v[50:51], v[50:51], v[182:183] op_sel_hi:[1,0]
	v_pk_mul_f32 v[52:53], v[52:53], v[182:183] op_sel_hi:[1,0]
	v_pk_mul_f32 v[62:63], v[62:63], v[142:143]
	v_pk_mul_f32 v[64:65], v[64:65], v[144:145]
	v_pk_mul_f32 v[58:59], v[58:59], v[138:139]
	v_pk_mul_f32 v[60:61], v[60:61], v[140:141]
	v_pk_mul_f32 v[54:55], v[54:55], v[134:135]
	v_pk_mul_f32 v[56:57], v[56:57], v[136:137]
	v_pk_mul_f32 v[50:51], v[50:51], v[130:131]
	v_pk_mul_f32 v[52:53], v[52:53], v[132:133]
	s_cmp_eq_u32 s20, 0
	s_cbranch_scc1 .Lwin_norope_4
	v_pk_mul_f32 v[192:193], v[54:55], v[106:107]
	v_pk_mul_f32 v[194:195], v[56:57], v[108:109]
	v_pk_mul_f32 v[54:55], v[54:55], v[98:99]
	v_pk_mul_f32 v[56:57], v[56:57], v[100:101]
	v_pk_fma_f32 v[54:55], v[62:63], v[106:107], v[54:55]
	v_pk_fma_f32 v[56:57], v[64:65], v[108:109], v[56:57]
	v_pk_fma_f32 v[62:63], v[62:63], v[98:99], v[192:193] neg_lo:[0,0,1] neg_hi:[0,0,1]
	v_pk_fma_f32 v[64:65], v[64:65], v[100:101], v[194:195] neg_lo:[0,0,1] neg_hi:[0,0,1]
	v_pk_mul_f32 v[192:193], v[50:51], v[110:111]
	v_pk_mul_f32 v[194:195], v[52:53], v[112:113]
	v_pk_mul_f32 v[50:51], v[50:51], v[102:103]
	v_pk_mul_f32 v[52:53], v[52:53], v[104:105]
	v_pk_fma_f32 v[50:51], v[58:59], v[110:111], v[50:51]
	v_pk_fma_f32 v[52:53], v[60:61], v[112:113], v[52:53]
	v_pk_fma_f32 v[58:59], v[58:59], v[102:103], v[192:193] neg_lo:[0,0,1] neg_hi:[0,0,1]
	v_pk_fma_f32 v[60:61], v[60:61], v[104:105], v[194:195] neg_lo:[0,0,1] neg_hi:[0,0,1]
.Lwin_norope_4:
	v_cvt_pk_bf16_f32 v62, v62, v63
	v_cvt_pk_bf16_f32 v63, v64, v65
	v_cvt_pk_bf16_f32 v64, v58, v59
	v_cvt_pk_bf16_f32 v65, v60, v61
	v_cvt_pk_bf16_f32 v54, v54, v55
	v_cvt_pk_bf16_f32 v55, v56, v57
	v_cvt_pk_bf16_f32 v56, v50, v51
	v_cvt_pk_bf16_f32 v57, v52, v53
	s_lshl_b32 s27, 128, s13
	v_add_u32_e32 v237, s27, v236
	global_store_dwordx4 v237, v[62:65], s[48:49]
	global_store_dwordx4 v237, v[54:57], s[48:49] offset:64
	v_add_u32_e32 v234, 0x5800, v235
	global_load_dwordx4 v[50:53], v234, s[78:79] offset:0
	global_load_dwordx4 v[54:57], v234, s[78:79] offset:16
	global_load_dwordx4 v[58:61], v234, s[22:23] offset:0
	global_load_dwordx4 v[62:65], v234, s[22:23] offset:16
	s_waitcnt vmcnt(12)
	v_pk_mul_f32 v[46:47], v[46:47], v[182:183] op_sel:[0,1] op_sel_hi:[1,1]
	v_pk_mul_f32 v[48:49], v[48:49], v[182:183] op_sel:[0,1] op_sel_hi:[1,1]
	v_pk_mul_f32 v[42:43], v[42:43], v[182:183] op_sel:[0,1] op_sel_hi:[1,1]
	v_pk_mul_f32 v[44:45], v[44:45], v[182:183] op_sel:[0,1] op_sel_hi:[1,1]
	v_pk_mul_f32 v[38:39], v[38:39], v[182:183] op_sel:[0,1] op_sel_hi:[1,1]
	v_pk_mul_f32 v[40:41], v[40:41], v[182:183] op_sel:[0,1] op_sel_hi:[1,1]
	v_pk_mul_f32 v[34:35], v[34:35], v[182:183] op_sel:[0,1] op_sel_hi:[1,1]
	v_pk_mul_f32 v[36:37], v[36:37], v[182:183] op_sel:[0,1] op_sel_hi:[1,1]
	v_pk_mul_f32 v[46:47], v[46:47], v[142:143]
	v_pk_mul_f32 v[48:49], v[48:49], v[144:145]
	v_pk_mul_f32 v[42:43], v[42:43], v[138:139]
	v_pk_mul_f32 v[44:45], v[44:45], v[140:141]
	v_pk_mul_f32 v[38:39], v[38:39], v[134:135]
	v_pk_mul_f32 v[40:41], v[40:41], v[136:137]
	v_pk_mul_f32 v[34:35], v[34:35], v[130:131]
	v_pk_mul_f32 v[36:37], v[36:37], v[132:133]
	s_cmp_eq_u32 s20, 0
	s_cbranch_scc1 .Lwin_norope_5
	v_pk_mul_f32 v[192:193], v[38:39], v[90:91]
	v_pk_mul_f32 v[194:195], v[40:41], v[92:93]
	v_pk_mul_f32 v[38:39], v[38:39], v[82:83]
	v_pk_mul_f32 v[40:41], v[40:41], v[84:85]
	v_pk_fma_f32 v[38:39], v[46:47], v[90:91], v[38:39]
	v_pk_fma_f32 v[40:41], v[48:49], v[92:93], v[40:41]
	v_pk_fma_f32 v[46:47], v[46:47], v[82:83], v[192:193] neg_lo:[0,0,1] neg_hi:[0,0,1]
	v_pk_fma_f32 v[48:49], v[48:49], v[84:85], v[194:195] neg_lo:[0,0,1] neg_hi:[0,0,1]
	v_pk_mul_f32 v[192:193], v[34:35], v[94:95]
	v_pk_mul_f32 v[194:195], v[36:37], v[96:97]
	v_pk_mul_f32 v[34:35], v[34:35], v[86:87]
	v_pk_mul_f32 v[36:37], v[36:37], v[88:89]
	v_pk_fma_f32 v[34:35], v[42:43], v[94:95], v[34:35]
	v_pk_fma_f32 v[36:37], v[44:45], v[96:97], v[36:37]
	v_pk_fma_f32 v[42:43], v[42:43], v[86:87], v[192:193] neg_lo:[0,0,1] neg_hi:[0,0,1]
	v_pk_fma_f32 v[44:45], v[44:45], v[88:89], v[194:195] neg_lo:[0,0,1] neg_hi:[0,0,1]
.Lwin_norope_5:
	v_cvt_pk_bf16_f32 v46, v46, v47
	v_cvt_pk_bf16_f32 v47, v48, v49
	v_cvt_pk_bf16_f32 v48, v42, v43
	v_cvt_pk_bf16_f32 v49, v44, v45
	v_cvt_pk_bf16_f32 v38, v38, v39
	v_cvt_pk_bf16_f32 v39, v40, v41
	v_cvt_pk_bf16_f32 v40, v34, v35
	v_cvt_pk_bf16_f32 v41, v36, v37
	s_lshl_b32 s27, 144, s13
	v_add_u32_e32 v237, s27, v236
	global_store_dwordx4 v237, v[46:49], s[48:49]
	global_store_dwordx4 v237, v[38:41], s[48:49] offset:64
	s_waitcnt vmcnt(8)
	v_pk_mul_f32 v[30:31], v[30:31], v[184:185] op_sel_hi:[1,0]
	v_pk_mul_f32 v[32:33], v[32:33], v[184:185] op_sel_hi:[1,0]
	v_pk_mul_f32 v[26:27], v[26:27], v[184:185] op_sel_hi:[1,0]
	v_pk_mul_f32 v[28:29], v[28:29], v[184:185] op_sel_hi:[1,0]
	v_pk_mul_f32 v[22:23], v[22:23], v[184:185] op_sel_hi:[1,0]
	v_pk_mul_f32 v[24:25], v[24:25], v[184:185] op_sel_hi:[1,0]
	v_pk_mul_f32 v[18:19], v[18:19], v[184:185] op_sel_hi:[1,0]
	v_pk_mul_f32 v[20:21], v[20:21], v[184:185] op_sel_hi:[1,0]
	v_pk_mul_f32 v[30:31], v[30:31], v[142:143]
	v_pk_mul_f32 v[32:33], v[32:33], v[144:145]
	v_pk_mul_f32 v[26:27], v[26:27], v[138:139]
	v_pk_mul_f32 v[28:29], v[28:29], v[140:141]
	v_pk_mul_f32 v[22:23], v[22:23], v[134:135]
	v_pk_mul_f32 v[24:25], v[24:25], v[136:137]
	v_pk_mul_f32 v[18:19], v[18:19], v[130:131]
	v_pk_mul_f32 v[20:21], v[20:21], v[132:133]
	s_cmp_eq_u32 s20, 0
	s_cbranch_scc1 .Lwin_norope_6
	v_pk_mul_f32 v[192:193], v[22:23], v[74:75]
	v_pk_mul_f32 v[194:195], v[24:25], v[76:77]
	v_pk_mul_f32 v[22:23], v[22:23], v[66:67]
	v_pk_mul_f32 v[24:25], v[24:25], v[68:69]
	v_pk_fma_f32 v[22:23], v[30:31], v[74:75], v[22:23]
	v_pk_fma_f32 v[24:25], v[32:33], v[76:77], v[24:25]
	v_pk_fma_f32 v[30:31], v[30:31], v[66:67], v[192:193] neg_lo:[0,0,1] neg_hi:[0,0,1]
	v_pk_fma_f32 v[32:33], v[32:33], v[68:69], v[194:195] neg_lo:[0,0,1] neg_hi:[0,0,1]
	v_pk_mul_f32 v[192:193], v[18:19], v[78:79]
	v_pk_mul_f32 v[194:195], v[20:21], v[80:81]
	v_pk_mul_f32 v[18:19], v[18:19], v[70:71]
	v_pk_mul_f32 v[20:21], v[20:21], v[72:73]
	v_pk_fma_f32 v[18:19], v[26:27], v[78:79], v[18:19]
	v_pk_fma_f32 v[20:21], v[28:29], v[80:81], v[20:21]
	v_pk_fma_f32 v[26:27], v[26:27], v[70:71], v[192:193] neg_lo:[0,0,1] neg_hi:[0,0,1]
	v_pk_fma_f32 v[28:29], v[28:29], v[72:73], v[194:195] neg_lo:[0,0,1] neg_hi:[0,0,1]
.Lwin_norope_6:
	v_cvt_pk_bf16_f32 v30, v30, v31
	v_cvt_pk_bf16_f32 v31, v32, v33
	v_cvt_pk_bf16_f32 v32, v26, v27
	v_cvt_pk_bf16_f32 v33, v28, v29
	v_cvt_pk_bf16_f32 v22, v22, v23
	v_cvt_pk_bf16_f32 v23, v24, v25
	v_cvt_pk_bf16_f32 v24, v18, v19
	v_cvt_pk_bf16_f32 v25, v20, v21
	s_lshl_b32 s27, 160, s13
	v_add_u32_e32 v237, s27, v236
	global_store_dwordx4 v237, v[30:33], s[48:49]
	global_store_dwordx4 v237, v[22:25], s[48:49] offset:64
	s_waitcnt vmcnt(4)
	v_pk_mul_f32 v[14:15], v[14:15], v[184:185] op_sel:[0,1] op_sel_hi:[1,1]
	v_pk_mul_f32 v[16:17], v[16:17], v[184:185] op_sel:[0,1] op_sel_hi:[1,1]
	v_pk_mul_f32 v[10:11], v[10:11], v[184:185] op_sel:[0,1] op_sel_hi:[1,1]
	v_pk_mul_f32 v[12:13], v[12:13], v[184:185] op_sel:[0,1] op_sel_hi:[1,1]
	v_pk_mul_f32 v[6:7], v[6:7], v[184:185] op_sel:[0,1] op_sel_hi:[1,1]
	v_pk_mul_f32 v[8:9], v[8:9], v[184:185] op_sel:[0,1] op_sel_hi:[1,1]
	v_pk_mul_f32 v[2:3], v[2:3], v[184:185] op_sel:[0,1] op_sel_hi:[1,1]
	v_pk_mul_f32 v[4:5], v[4:5], v[184:185] op_sel:[0,1] op_sel_hi:[1,1]
	v_pk_mul_f32 v[14:15], v[14:15], v[142:143]
	v_pk_mul_f32 v[16:17], v[16:17], v[144:145]
	v_pk_mul_f32 v[10:11], v[10:11], v[138:139]
	v_pk_mul_f32 v[12:13], v[12:13], v[140:141]
	v_pk_mul_f32 v[6:7], v[6:7], v[134:135]
	v_pk_mul_f32 v[8:9], v[8:9], v[136:137]
	v_pk_mul_f32 v[2:3], v[2:3], v[130:131]
	v_pk_mul_f32 v[4:5], v[4:5], v[132:133]
	s_cmp_eq_u32 s20, 0
	s_cbranch_scc1 .Lwin_norope_7
	v_pk_mul_f32 v[192:193], v[6:7], v[58:59]
	v_pk_mul_f32 v[194:195], v[8:9], v[60:61]
	v_pk_mul_f32 v[6:7], v[6:7], v[50:51]
	v_pk_mul_f32 v[8:9], v[8:9], v[52:53]
	v_pk_fma_f32 v[6:7], v[14:15], v[58:59], v[6:7]
	v_pk_fma_f32 v[8:9], v[16:17], v[60:61], v[8:9]
	v_pk_fma_f32 v[14:15], v[14:15], v[50:51], v[192:193] neg_lo:[0,0,1] neg_hi:[0,0,1]
	v_pk_fma_f32 v[16:17], v[16:17], v[52:53], v[194:195] neg_lo:[0,0,1] neg_hi:[0,0,1]
	v_pk_mul_f32 v[192:193], v[2:3], v[62:63]
	v_pk_mul_f32 v[194:195], v[4:5], v[64:65]
	v_pk_mul_f32 v[2:3], v[2:3], v[54:55]
	v_pk_mul_f32 v[4:5], v[4:5], v[56:57]
	v_pk_fma_f32 v[2:3], v[10:11], v[62:63], v[2:3]
	v_pk_fma_f32 v[4:5], v[12:13], v[64:65], v[4:5]
	v_pk_fma_f32 v[10:11], v[10:11], v[54:55], v[192:193] neg_lo:[0,0,1] neg_hi:[0,0,1]
	v_pk_fma_f32 v[12:13], v[12:13], v[56:57], v[194:195] neg_lo:[0,0,1] neg_hi:[0,0,1]
.Lwin_norope_7:
	v_cvt_pk_bf16_f32 v14, v14, v15
	v_cvt_pk_bf16_f32 v15, v16, v17
	v_cvt_pk_bf16_f32 v16, v10, v11
	v_cvt_pk_bf16_f32 v17, v12, v13
	v_cvt_pk_bf16_f32 v6, v6, v7
	v_cvt_pk_bf16_f32 v7, v8, v9
	v_cvt_pk_bf16_f32 v8, v2, v3
	v_cvt_pk_bf16_f32 v9, v4, v5
	s_lshl_b32 s27, 176, s13
	v_add_u32_e32 v237, s27, v236
	global_store_dwordx4 v237, v[14:17], s[48:49]
	global_store_dwordx4 v237, v[6:9], s[48:49] offset:64
	s_mov_b64 s[58:59], 0
